# phase 3: odd workgroups walk their four items in reverse (ret_kv first) to de-correlate load bursts; no setprio
# baseline (speedup 1.0000x reference)
; #define LAS __attribute__((address_space(3)))
; #define LAUNDER() int t2 = tid; asm volatile("" : "+v"(t2)); const int w2 = __builtin_amdgcn_readfirstlane(t2 >> 6), l2 = t2 & 63; (void)w2; (void)l2;
; template <bool FIRST>
; __device__ __forceinline__ void swa_item(const Params& p, int l, LAS unsigned char* lds, int item, int tid, int wave, int lane) {
;     const int b = item >> 8, nb = (item >> 3) & 31, kvh = item & 7, tb = b * SEQ + nb * 128;
;     const half_t* PR = (const half_t*)(p.ws + WS_PROJ);
;     LAS half_t* Ks = (LAS half_t*)lds; LAS half_t* Vs = (LAS half_t*)(lds + SV_OFF);
;     const h8 z8 = {0, 0, 0, 0, 0, 0, 0, 0};
;     const int g = lane >> 4, r = lane & 15, q = (lane & 15) >> 2, pp = lane & 3;
;     const int tok = tb + wave * 16 + r;
;     h8 qfa[4][2];
; #pragma unroll
;     for (int gi = 0; gi < 4; ++gi)
; #pragma unroll
;         for (int ks = 0; ks < 2; ++ks) qfa[gi][ks] = *(const h8*)(PR + (size_t)tok * NIN + C_SQ + (kvh * 4 + gi) * 64 + ks * 32 + g * 8);
; #pragma unroll
;     for (int i = 0; i < 4; ++i) { const int id = tid + 512 * i, row = id >> 3, ch = id & 7;
;         h8 kk = z8, vv = z8;
;         if (nb > 0 || row >= 128) { const half_t* src = PR + (size_t)(tb - 128 + row) * NIN + kvh * 64 + ch * 8; kk = *(const h8*)(src + C_SK); vv = *(const h8*)(src + C_SV); }
;         *(LAS h8*)(Ks + row * SSTR + ch * 8) = kk; *(LAS h8*)(Vs + row * SSTR + ch * 8) = vv; }
;     if (tid < 128) { const int row = 256 + (tid >> 3), ch = tid & 7; *(LAS h8*)(Ks + row * SSTR + ch * 8) = z8; *(LAS h8*)(Vs + row * SSTR + ch * 8) = z8; }
;     __syncthreads();
; __global__ void __launch_bounds__(512, 2) hybrid_fwd(Params p) {
;     ...
;         { LAUNDER(); for (int it = blockIdx.x; it < 1024; it += G) { if (it < 512) { if (((it >> 3) & 31) == 0) swa_item<true>(p, l, lds, it, t2, w2, l2); else swa_item<false>(p, l, lds, it, t2, w2, l2); } else ret_kv_item(p, lds, it - 512, t2, w2, l2); } }
.LBB0_385:
	s_or_b64 exec, exec, s[0:1]
	v_readlane_b32 s0, v253, 18
	s_waitcnt lgkmcnt(0)
	v_mov_b32_e32 v0, v180
	v_readlane_b32 s1, v253, 19
	s_barrier
	s_andn2_b64 vcc, exec, s[0:1]
	v_readfirstlane_b32 s0, v0
	v_readlane_b32 s18, v253, 20
	v_readlane_b32 s19, v253, 21
	s_cbranch_vccnz .LBB0_417
	v_lshlrev_b32_e32 v5, 3, v0
	s_ashr_i32 s4, s0, 6
	v_and_b32_e32 v4, 56, v5
	v_readlane_b32 s0, v252, 12
	v_lshlrev_b32_e32 v2, 2, v4
	v_readlane_b32 s1, v252, 13
	v_ashrrev_i32_e32 v75, 3, v0
	s_movk_i32 s5, 0x110
	v_lshl_add_u64 v[68:69], s[0:1], 0, v[2:3]
	v_sub_u32_e32 v2, 0x7f, v75
	v_cvt_f32_i32_e32 v90, v2
	v_lshlrev_b32_e32 v2, 1, v4
	v_add_u32_e32 v6, 0, v2
	v_mad_u64_u32 v[70:71], s[0:1], v75, s5, v[6:7]
	v_add_u32_e32 v7, 0x200, v0
	v_ashrrev_i32_e32 v71, 3, v7
	v_mad_u64_u32 v[72:73], s[0:1], v71, s5, v[6:7]
	v_add_u32_e32 v11, 0x400, v0
	v_add_u32_e32 v13, 0x600, v0
	v_add_u32_e32 v15, 0x800, v0
	v_add_u32_e32 v16, 0xa00, v0
	v_add_u32_e32 v17, 0xc00, v0
	v_add_u32_e32 v18, 0xe00, v0
	v_sub_u32_e32 v8, 0x7f, v71
	v_ashrrev_i32_e32 v73, 5, v0
	s_movk_i32 s0, 0x220
	v_ashrrev_i32_e32 v92, 5, v7
	v_ashrrev_i32_e32 v93, 5, v11
	v_ashrrev_i32_e32 v94, 5, v13
	v_ashrrev_i32_e32 v95, 5, v15
	v_ashrrev_i32_e32 v96, 5, v16
	v_ashrrev_i32_e32 v97, 5, v17
	v_ashrrev_i32_e32 v98, 5, v18
	s_lshl_b32 s5, s4, 5
	v_cvt_f32_i32_e32 v91, v8
	v_and_b32_e32 v8, 0xf8, v5
	v_mul_lo_u32 v10, v73, s0
	v_mul_lo_u32 v7, v92, s0
	v_mul_lo_u32 v12, v93, s0
	v_mul_lo_u32 v14, v94, s0
	v_mul_lo_u32 v15, v95, s0
	v_mul_lo_u32 v16, v96, s0
	v_mul_lo_u32 v17, v97, s0
	v_mul_lo_u32 v18, v98, s0
	s_add_i32 s0, s5, 0
	v_and_b32_e32 v5, 24, v5
	s_movk_i32 s10, 0x90
	v_add_u32_e32 v22, s0, v5
	v_mad_u64_u32 v[78:79], s[0:1], v71, s10, v[6:7]
	v_ashrrev_i32_e32 v79, 3, v11
	v_mad_u64_u32 v[80:81], s[0:1], v79, s10, v[6:7]
	v_ashrrev_i32_e32 v81, 3, v13
	v_mad_u64_u32 v[82:83], s[0:1], v81, s10, v[6:7]
	s_lshl_b32 s9, s4, 4
	s_movk_i32 s0, 0x80
	v_and_b32_e32 v20, 15, v0
	v_mul_lo_u32 v25, v75, s10
	v_cmp_gt_i32_e64 s[46:47], s0, v0
	s_add_i32 s0, s9, 16
	v_add_u32_e32 v101, v6, v25
	v_or_b32_e32 v6, s0, v20
	s_add_i32 s0, s9, 32
	v_mul_lo_u32 v107, v6, s10
	v_or_b32_e32 v6, s0, v20
	s_add_i32 s0, s9, 48
	v_mul_lo_u32 v108, v6, s10
	v_or_b32_e32 v6, s0, v20
	s_add_i32 s0, s9, 64
	v_and_b32_e32 v1, 63, v0
	v_bfe_u32 v19, v0, 4, 2
	v_mul_lo_u32 v109, v6, s10
	v_or_b32_e32 v6, s0, v20
	s_add_i32 s0, s9, 0x50
	v_bfe_u32 v21, v0, 2, 2
	v_lshlrev_b32_e32 v99, 2, v19
	v_lshlrev_b32_e32 v1, 2, v1
	v_mul_lo_u32 v110, v6, s10
	v_or_b32_e32 v6, s0, v20
	s_add_i32 s0, s9, 0x60
	v_or_b32_e32 v100, s9, v20
	v_lshl_add_u64 v[76:77], s[36:37], 0, v[2:3]
	v_add3_u32 v83, 0, v25, v2
	v_and_b32_e32 v2, 48, v0
	s_lshl_b32 s8, s22, 5
	v_xor_b32_e32 v104, 64, v1
	v_xor_b32_e32 v105, 0x80, v1
	v_or3_b32 v1, v21, s9, v99
	v_mul_lo_u32 v111, v6, s10
	v_or_b32_e32 v6, s0, v20
	s_add_i32 s0, s9, 0x70
	s_addk_i32 s9, 0x80
	v_add_u32_e32 v103, 0, v2
	v_sub_u32_e32 v2, v20, v99
	s_cmp_gt_i32 s4, 7
	v_mul_lo_u32 v112, v6, s10
	v_or_b32_e32 v6, s0, v20
	v_cmp_gt_i32_e64 s[48:49], 0, v2
	v_cmp_gt_i32_e64 s[50:51], 1, v2
	v_cmp_gt_i32_e64 s[52:53], 2, v2
	v_cmp_gt_i32_e64 s[54:55], 3, v2
	s_cselect_b64 s[0:1], -1, 0
	s_and_b64 s[56:57], s[0:1], s[48:49]
	s_and_b64 s[58:59], s[0:1], s[50:51]
	s_and_b64 s[24:25], s[0:1], s[52:53]
	s_and_b64 s[62:63], s[0:1], s[54:55]
	s_cmp_gt_i32 s4, 6
	s_cselect_b64 s[64:65], -1, 0
	s_cmp_gt_i32 s4, 5
	s_cselect_b64 s[66:67], -1, 0
	s_cmp_gt_i32 s4, 4
	s_cselect_b64 s[68:69], -1, 0
	s_cmp_gt_i32 s4, 3
	v_lshlrev_b32_e32 v74, 3, v19
	s_cselect_b64 s[70:71], -1, 0
	s_cmp_gt_i32 s4, 2
	v_or_b32_e32 v23, v74, v21
	s_cselect_b64 s[72:73], -1, 0
	s_cmp_gt_i32 s4, 1
	v_lshrrev_b32_e32 v0, 1, v0
	v_mul_u32_u24_e32 v24, 0x110, v23
	v_mul_u32_u24_e32 v23, 0x220, v23
	v_mul_lo_u32 v1, v1, s10
	s_cselect_b64 s[74:75], -1, 0
	s_cmp_gt_i32 s4, 0
	v_and_b32_e32 v0, 16, v0
	v_lshl_add_u32 v9, v8, 1, 0
	v_and_b32_e32 v19, 4, v99
	s_movk_i32 s6, 0x7f
	v_mul_lo_u32 v113, v6, s10
	v_or_b32_e32 v6, s9, v20
	v_add3_u32 v115, 0, v5, v1
	s_cselect_b64 s[76:77], -1, 0
	s_cmp_gt_i32 s4, -1
	v_or_b32_e32 v1, v23, v5
	v_or3_b32 v0, s5, v0, v20
	v_cmp_lt_i32_e64 s[38:39], s6, v75
	v_add_u32_e32 v102, 0x9900, v101
	v_cmp_lt_i32_e64 s[40:41], s6, v71
	v_cmp_lt_i32_e64 s[42:43], s6, v79
	v_cmp_lt_i32_e64 s[6:7], s6, v81
	v_mul_lo_u32 v106, v100, s10
	v_mul_lo_u32 v114, v6, s10
	s_cselect_b64 s[78:79], -1, 0
	v_add_u32_e32 v116, 0, v1
	v_lshl_or_b32 v117, v0, 3, v19
	v_lshlrev_b32_e32 v84, 1, v4
	v_lshlrev_b32_e32 v86, 1, v8
	v_add_u32_e32 v118, v9, v10
	v_add_u32_e32 v119, v9, v7
	v_add_u32_e32 v120, v9, v12
	v_add_u32_e32 v121, v9, v14
	v_add_u32_e32 v122, v9, v15
	v_add_u32_e32 v123, v9, v16
	v_add_u32_e32 v124, v9, v17
	v_add_u32_e32 v125, v9, v18
	v_add_u32_e32 v126, v22, v24
	s_mov_b32 s9, s2
	s_mov_b32 s99, s28
	s_cmpk_lg_i32 s28, 0x100
	s_cbranch_scc1 .Litem_fwd
	s_bitcmp1_b32 s2, 0
	s_cbranch_scc0 .Litem_fwd
	s_add_i32 s9, s2, 0x300
	s_sub_i32 s99, 0, s28
.Litem_fwd:
	s_branch .LBB0_389

; #define LAUNDER() int t2 = tid; asm volatile("" : "+v"(t2)); const int w2 = __builtin_amdgcn_readfirstlane(t2 >> 6), l2 = t2 & 63; (void)w2; (void)l2;
; __global__ void __launch_bounds__(512, 2) hybrid_fwd(Params p) {
;     ...
;         { LAUNDER(); for (int it = blockIdx.x; it < 1024; it += G) { if (it < 512) { if (((it >> 3) & 31) == 0) swa_item<true>(p, l, lds, it, t2, w2, l2); else swa_item<false>(p, l, lds, it, t2, w2, l2); } else ret_kv_item(p, lds, it - 512, t2, w2, l2); } }
.LBB0_388:
	s_add_i32 s9, s9, s99
	s_cmp_gt_u32 s9, 0x3ff
	s_cbranch_scc1 .LBB0_417
